# nsa window loop: global->register prefetch two tiles ahead with a second staging register set
# baseline (speedup 1.0000x reference)
.LBB0_1462:
	s_or_b64 exec, exec, s[10:11]
	s_add_i32 s10, s55, 0xfffffe01
	s_ashr_i32 s10, s10, 6
	s_cmpk_gt_u32 s55, 0x1fe
	s_cselect_b32 s10, s10, 0
	s_sub_i32 s14, s72, s10
	s_add_i32 s14, s14, 1
	s_cmp_lt_i32 s14, 1
	s_cbranch_scc1 .LBB0_1416
	s_lshl_b64 s[12:13], s[66:67], 21
	s_add_u32 s15, s8, s12
	s_addc_u32 s21, s9, s13
	s_add_u32 s18, s26, s12
	s_addc_u32 s19, s27, s13
	s_ashr_i32 s11, s10, 31
	s_lshl_b64 s[16:17], s[10:11], 14
	s_add_u32 s18, s18, s16
	s_addc_u32 s19, s19, s17
	s_add_u32 s20, s15, s16
	s_addc_u32 s21, s21, s17
	v_mov_b32_e32 v87, v1
	v_lshl_add_u64 v[52:53], s[20:21], 0, v[86:87]
	v_lshl_add_u64 v[54:55], s[18:19], 0, v[86:87]
	v_lshlrev_b64 v[56:57], 1, v[88:89]
	v_lshl_add_u64 v[58:59], v[52:53], 0, v[56:57]
	v_lshl_add_u64 v[56:57], v[54:55], 0, v[56:57]
	global_load_dwordx4 v[84:87], v[58:59], off
	global_load_dwordx4 v[88:91], v[56:57], off
	v_lshlrev_b64 v[56:57], 1, v[92:93]
	v_lshl_add_u64 v[52:53], v[52:53], 0, v[56:57]
	v_lshl_add_u64 v[54:55], v[54:55], 0, v[56:57]
	global_load_dwordx4 v[92:95], v[52:53], off
	global_load_dwordx4 v[96:99], v[54:55], off
	v_lshl_add_u64 v[198:199], v[58:59], 0, s[64:65]
	s_sub_u32 s78, s18, s20
	s_subb_u32 s79, s19, s21
	v_lshl_add_u64 v[202:203], v[52:53], 0, s[64:65]
	v_lshl_add_u64 v[204:205], v[54:55], 0, s[64:65]
	v_lshl_add_u64 v[200:201], v[198:199], 0, s[78:79]
	s_lshl_b32 s15, s10, 6
	s_sub_i32 s10, s55, 51
	v_add3_u32 v80, s10, v105, v104
	s_add_u32 s10, s12, s16
	s_addc_u32 s13, s13, s17
	v_sub_u32_e32 v146, v141, v2
	v_mov_b32_e32 v2, v1
	v_mov_b32_e32 v3, v1
	v_sub_u32_e32 v80, v80, v141
	s_add_u32 s12, s52, s10
	v_mov_b32_e32 v0, v1
	v_mov_b64_e32 v[54:55], v[2:3]
	v_mov_b64_e32 v[58:59], v[2:3]
	s_waitcnt vmcnt(5)
	v_mov_b64_e32 v[62:63], v[2:3]
	s_waitcnt vmcnt(4)
	v_mov_b64_e32 v[66:67], v[2:3]
	v_mov_b64_e32 v[70:71], v[2:3]
	v_mov_b64_e32 v[74:75], v[2:3]
	v_mov_b64_e32 v[78:79], v[2:3]
	v_subrev_u32_e32 v147, s15, v80
	s_addc_u32 s13, s53, s13
	v_mov_b64_e32 v[82:83], v[2:3]
	v_add_u32_e32 v145, 0xfffffe04, v134
	s_mov_b32 s11, 0
	v_mov_b32_e32 v148, 0xc6ea6000
	v_mov_b32_e32 v144, 0
	v_mov_b64_e32 v[52:53], v[0:1]
	v_mov_b64_e32 v[56:57], v[0:1]
	v_mov_b64_e32 v[60:61], v[0:1]
	v_mov_b64_e32 v[64:65], v[0:1]
	v_mov_b64_e32 v[68:69], v[0:1]
	v_mov_b64_e32 v[72:73], v[0:1]
	v_mov_b64_e32 v[76:77], v[0:1]
	v_lshl_add_u64 v[128:129], s[12:13], 0, v[100:101]
	v_lshl_add_u64 v[130:131], s[12:13], 0, v[102:103]
	v_mov_b64_e32 v[80:81], v[0:1]
	s_waitcnt vmcnt(3)
	ds_write_b128 v107, v[84:87]
	s_waitcnt vmcnt(2)
	ds_write_b128 v107, v[88:91] offset:18432
	s_waitcnt vmcnt(1)
	ds_write_b128 v106, v[92:95]
	s_waitcnt vmcnt(0)
	ds_write_b128 v106, v[96:99] offset:18432
	s_mov_b32 s84, 0x10108000
	s_mov_b32 s85, 0
	s_mov_b32 s86, 0x11108000
	s_mov_b32 s87, 0
	s_cmp_lt_i32 s14, 2
	s_cbranch_scc1 .Lw2_no1
	global_load_dwordx4 v[182:185], v[198:199], off
	global_load_dwordx4 v[186:189], v[200:201], off
	global_load_dwordx4 v[190:193], v[202:203], off
	global_load_dwordx4 v[194:197], v[204:205], off

.LBB0_1464:
	s_add_i32 s16, s11, 1
	s_cmp_lt_i32 s16, s14
	s_cselect_b64 s[12:13], -1, 0
	s_add_i32 s78, s16, 1
	s_cmp_ge_i32 s78, s14
	s_cbranch_scc1 .LBB0_1466
	v_lshl_add_u64 v[2:3], v[128:129], 0, v[126:127]
	v_lshl_add_u64 v[100:101], v[130:131], 0, v[126:127]
	v_lshl_add_u64 v[102:103], v[2:3], 0, s[84:85]
	v_lshl_add_u64 v[2:3], v[2:3], 0, s[86:87]
	v_lshl_add_u64 v[104:105], v[100:101], 0, s[84:85]
	v_lshl_add_u64 v[100:101], v[100:101], 0, s[86:87]
	s_bitcmp1_b32 s11, 0
	s_cbranch_scc1 .Lw2_ld_odd
	global_load_dwordx4 v[84:87], v[102:103], off
	global_load_dwordx4 v[88:91], v[2:3], off
	global_load_dwordx4 v[92:95], v[104:105], off
	global_load_dwordx4 v[96:99], v[100:101], off
	s_branch .LBB0_1466
.Lw2_ld_odd:
	global_load_dwordx4 v[182:185], v[102:103], off
	global_load_dwordx4 v[186:189], v[2:3], off
	global_load_dwordx4 v[190:193], v[104:105], off
	global_load_dwordx4 v[194:197], v[100:101], off

.LBB0_1470:
	v_sub_f32_e32 v100, v154, v148
	v_sub_f32_e32 v101, v155, v148
	v_sub_f32_e32 v102, v160, v148
	v_sub_f32_e32 v103, v159, v148
	v_sub_f32_e32 v104, v158, v148
	v_sub_f32_e32 v105, v157, v148
	v_sub_f32_e32 v106, v161, v148
	v_sub_f32_e32 v107, v156, v148
	v_exp_f32_e32 v100, v100
	v_exp_f32_e32 v101, v101
	v_exp_f32_e32 v102, v102
	v_exp_f32_e32 v103, v103
	v_exp_f32_e32 v104, v104
	v_exp_f32_e32 v105, v105
	v_exp_f32_e32 v106, v106
	v_exp_f32_e32 v107, v107
	v_add3_u32 v170, s17, v143, v142
	ds_read_b64_tr_b16 v[110:111], v170 offset:23040
	ds_read_b64_tr_b16 v[108:109], v170 offset:18432
	ds_read_b64_tr_b16 v[114:115], v170 offset:23072
	ds_read_b64_tr_b16 v[112:113], v170 offset:18464
	ds_read_b64_tr_b16 v[158:159], v170 offset:18496
	ds_read_b64_tr_b16 v[162:163], v170 offset:18528
	ds_read_b64_tr_b16 v[160:161], v170 offset:23104
	ds_read_b64_tr_b16 v[164:165], v170 offset:23136
	v_cvt_pk_bf16_f32 v154, v100, v101
	v_cvt_pk_bf16_f32 v155, v102, v103
	v_cvt_pk_bf16_f32 v156, v104, v105
	v_cvt_pk_bf16_f32 v157, v106, v107
	v_sub_f32_e32 v2, v2, v148
	v_sub_f32_e32 v3, v3, v148
	s_waitcnt lgkmcnt(4)
	v_mfma_f32_16x16x32_bf16 v[76:79], v[112:115], v[154:157], v[76:79]
	ds_read_b64_tr_b16 v[112:113], v170 offset:18560
	ds_read_b64_tr_b16 v[114:115], v170 offset:23168
	v_sub_f32_e32 v0, v0, v148
	v_exp_f32_e32 v2, v2
	v_mfma_f32_16x16x32_bf16 v[80:83], v[108:111], v[154:157], v[80:83]
	v_sub_f32_e32 v108, v153, v148
	v_sub_f32_e32 v109, v152, v148
	v_sub_f32_e32 v110, v151, v148
	s_waitcnt lgkmcnt(3)
	v_mfma_f32_16x16x32_bf16 v[72:75], v[158:161], v[154:157], v[72:75]
	v_sub_f32_e32 v111, v150, v148
	v_exp_f32_e32 v108, v108
	v_exp_f32_e32 v109, v109
	s_waitcnt lgkmcnt(2)
	v_mfma_f32_16x16x32_bf16 v[68:71], v[162:165], v[154:157], v[68:71]
	ds_read_b64_tr_b16 v[152:153], v170 offset:23200
	ds_read_b64_tr_b16 v[150:151], v170 offset:18592
	ds_read_b64_tr_b16 v[158:159], v170 offset:18624
	ds_read_b64_tr_b16 v[162:163], v170 offset:18656
	ds_read_b64_tr_b16 v[160:161], v170 offset:23232
	ds_read_b64_tr_b16 v[164:165], v170 offset:23264
	v_exp_f32_e32 v110, v110
	v_exp_f32_e32 v111, v111
	s_waitcnt lgkmcnt(6)
	v_mfma_f32_16x16x32_bf16 v[64:67], v[112:115], v[154:157], v[64:67]
	v_sub_f32_e32 v112, v149, v148
	v_exp_f32_e32 v112, v112
	v_exp_f32_e32 v3, v3
	s_waitcnt lgkmcnt(4)
	v_mfma_f32_16x16x32_bf16 v[60:63], v[150:153], v[154:157], v[60:63]
	v_exp_f32_e32 v0, v0
	v_cvt_pk_bf16_f32 v150, v108, v109
	v_cvt_pk_bf16_f32 v151, v110, v111
	s_waitcnt lgkmcnt(1)
	v_mfma_f32_16x16x32_bf16 v[56:59], v[158:161], v[154:157], v[56:59]
	v_cvt_pk_bf16_f32 v152, v112, v2
	v_cvt_pk_bf16_f32 v153, v3, v0
	s_andn2_b64 vcc, exec, s[12:13]
	s_waitcnt lgkmcnt(0)
	v_mfma_f32_16x16x32_bf16 v[52:55], v[162:165], v[154:157], v[52:55]
	ds_read_b64_tr_b16 v[154:155], v170 offset:27648
	ds_read_b64_tr_b16 v[156:157], v170 offset:32256
	ds_read_b64_tr_b16 v[160:161], v170 offset:32288
	ds_read_b64_tr_b16 v[158:159], v170 offset:27680
	ds_read_b64_tr_b16 v[162:163], v170 offset:27712
	ds_read_b64_tr_b16 v[166:167], v170 offset:27744
	ds_read_b64_tr_b16 v[164:165], v170 offset:32320
	ds_read_b64_tr_b16 v[168:169], v170 offset:32352
	s_waitcnt lgkmcnt(6)
	v_mfma_f32_16x16x32_bf16 v[80:83], v[154:157], v[150:153], v[80:83]
	ds_read_b64_tr_b16 v[154:155], v170 offset:27776
	ds_read_b64_tr_b16 v[156:157], v170 offset:32384
	s_waitcnt lgkmcnt(6)
	v_mfma_f32_16x16x32_bf16 v[76:79], v[158:161], v[150:153], v[76:79]
	s_waitcnt lgkmcnt(3)
	v_mfma_f32_16x16x32_bf16 v[72:75], v[162:165], v[150:153], v[72:75]
	s_waitcnt lgkmcnt(2)
	v_mfma_f32_16x16x32_bf16 v[68:71], v[166:169], v[150:153], v[68:71]
	ds_read_b64_tr_b16 v[160:161], v170 offset:32416
	ds_read_b64_tr_b16 v[158:159], v170 offset:27808
	ds_read_b64_tr_b16 v[162:163], v170 offset:27840
	ds_read_b64_tr_b16 v[166:167], v170 offset:27872
	ds_read_b64_tr_b16 v[164:165], v170 offset:32448
	ds_read_b64_tr_b16 v[168:169], v170 offset:32480
	s_waitcnt lgkmcnt(6)
	v_mfma_f32_16x16x32_bf16 v[64:67], v[154:157], v[150:153], v[64:67]
	s_waitcnt lgkmcnt(4)
	v_mfma_f32_16x16x32_bf16 v[60:63], v[158:161], v[150:153], v[60:63]
	s_waitcnt lgkmcnt(1)
	v_mfma_f32_16x16x32_bf16 v[56:59], v[162:165], v[150:153], v[56:59]
	s_waitcnt lgkmcnt(0)
	v_mfma_f32_16x16x32_bf16 v[52:55], v[166:169], v[150:153], v[52:55]
	s_cbranch_vccnz .LBB0_1472
	s_bitcmp1_b32 s16, 0
	s_cselect_b32 s10, 0x9000, 0
	v_add_u32_e32 v113, s10, v138
	v_add_u32_e32 v114, v113, v139
	v_add_u32_e32 v113, v113, v135
	s_add_i32 s78, s16, 1
	s_cmp_lt_i32 s78, s14
	s_cbranch_scc1 .Lw2_wait4
	s_waitcnt vmcnt(0)
	s_branch .Lw2_wr
.Lw2_wait4:
	s_waitcnt vmcnt(4)
.Lw2_wr:
	s_bitcmp1_b32 s16, 0
	s_cbranch_scc1 .Lw2_wr_odd
	ds_write_b128 v113, v[84:87]
	ds_write_b128 v113, v[88:91] offset:18432
	ds_write_b128 v114, v[92:95]
	ds_write_b128 v114, v[96:99] offset:18432
	s_branch .LBB0_1472
.Lw2_wr_odd:
	ds_write_b128 v113, v[182:185]
	ds_write_b128 v113, v[186:189] offset:18432
	ds_write_b128 v114, v[190:193]
	ds_write_b128 v114, v[194:197] offset:18432
